# P5 conv+gelu epilogue: the second weight-load group is waited for once, unconditionally; the seven per-step vmcnt(0) waits that only covered output stores become lgkmcnt waits
# speedup vs baseline: 1.0011x; 1.0011x over previous
.LBB0_1316:
	s_or_b64 exec, exec, s[2:3]
	v_or_b32_e32 v64, 4, v174
	v_ashrrev_i32_e32 v65, 31, v64
	v_lshlrev_b64 v[92:93], 2, v[64:65]
	v_lshl_add_u64 v[64:65], s[28:29], 0, v[92:93]
	v_lshl_add_u64 v[66:67], s[30:31], 0, v[92:93]
	global_load_dwordx4 v[72:75], v[188:189], off offset:16
	global_load_dwordx4 v[68:71], v[64:65], off
	s_nop 0
	global_load_dwordx4 v[64:67], v[66:67], off
	s_nop 0
	global_load_dwordx4 v[76:79], v[190:191], off offset:16
	v_lshl_add_u64 v[80:81], s[18:19], 0, v[92:93]
	v_lshl_add_u64 v[82:83], s[34:35], 0, v[92:93]
	v_lshl_add_u64 v[84:85], s[36:37], 0, v[92:93]
	v_lshl_add_u64 v[92:93], s[20:21], 0, v[92:93]
	global_load_dwordx4 v[88:91], v[80:81], off
	s_nop 0
	global_load_dwordx4 v[80:83], v[82:83], off
	v_mov_b32_e32 v187, v186
	global_load_dwordx4 v[84:87], v[84:85], off
	v_mov_b32_e32 v108, v186
	global_load_dwordx4 v[92:95], v[92:93], off
	v_mov_b32_e32 v109, v186
	v_pk_mul_f32 v[62:63], v[62:63], v[108:109]
	v_pk_mul_f32 v[60:61], v[60:61], v[186:187]
	v_pk_mul_f32 v[58:59], v[58:59], v[108:109]
	v_pk_mul_f32 v[56:57], v[56:57], v[186:187]
	ds_write_b128 v168, v[60:63]
	ds_write_b128 v168, v[56:59] offset:16384
	s_waitcnt vmcnt(0)
	s_and_saveexec_b64 s[2:3], s[8:9]
	s_cbranch_execz .LBB0_1318
	ds_read_b128 v[108:111], v185 offset:16384
	ds_read_b128 v[116:119], v183 offset:16384
	s_waitcnt lgkmcnt(0)
	v_pk_fma_f32 v[118:119], v[90:91], v[118:119], v[94:95]
	v_pk_fma_f32 v[116:117], v[88:89], v[116:117], v[92:93]
	v_pk_fma_f32 v[110:111], v[82:83], v[110:111], v[118:119]
	v_pk_fma_f32 v[108:109], v[80:81], v[108:109], v[116:117]
	v_pk_fma_f32 v[116:117], v[58:59], v[86:87], v[110:111]
	v_pk_fma_f32 v[118:119], v[56:57], v[84:85], v[108:109]
	ds_read_b128 v[56:59], v185
	ds_read_b128 v[108:111], v183
	s_waitcnt lgkmcnt(0)
	v_pk_fma_f32 v[108:109], v[72:73], v[108:109], v[76:77]
	s_nop 0
	v_pk_fma_f32 v[56:57], v[68:69], v[56:57], v[108:109]
	v_pk_fma_f32 v[110:111], v[74:75], v[110:111], v[78:79]
	v_pk_fma_f32 v[56:57], v[60:61], v[64:65], v[56:57]
	v_mul_f32_e32 v60, 0x3d372713, v118
	v_mul_f32_e32 v61, 0x3d372713, v119
	v_fma_f32 v60, v118, v60, 1.0
	v_fma_f32 v61, v119, v61, 1.0
	v_mul_f32_e32 v60, v118, v60
	v_mul_f32_e32 v61, v119, v61
	v_mul_f32_e32 v60, 0x3fcc422a, v60
	v_mul_f32_e32 v61, 0x3fcc422a, v61
	v_mul_f32_e32 v60, 0xbfb8aa3b, v60
	v_mul_f32_e32 v61, 0xbfb8aa3b, v61
	v_exp_f32_e32 v60, v60
	v_exp_f32_e32 v61, v61
	v_pk_fma_f32 v[58:59], v[70:71], v[58:59], v[110:111]
	v_add_f32_e32 v60, 1.0, v60
	v_add_f32_e32 v61, 1.0, v61
	v_rcp_f32_e32 v60, v60
	v_rcp_f32_e32 v61, v61
	v_pk_fma_f32 v[58:59], v[62:63], v[66:67], v[58:59]
	v_pk_mul_f32 v[60:61], v[118:119], v[60:61]
	s_nop 0
	v_pk_mul_f32 v[56:57], v[56:57], v[60:61]
	s_nop 0
	v_cvt_pk_bf16_f32 v56, v56, v57
	v_mul_f32_e32 v57, 0x3d372713, v116
	v_fma_f32 v57, v116, v57, 1.0
	v_mul_f32_e32 v57, v116, v57
	v_mul_f32_e32 v57, 0x3fcc422a, v57
	v_mul_f32_e32 v57, 0xbfb8aa3b, v57
	v_exp_f32_e32 v57, v57
	s_nop 0
	v_add_f32_e32 v57, 1.0, v57
	v_rcp_f32_e32 v60, v57
	v_mul_f32_e32 v57, 0x3d372713, v117
	v_fma_f32 v57, v117, v57, 1.0
	v_mul_f32_e32 v57, v117, v57
	v_mul_f32_e32 v57, 0x3fcc422a, v57
	v_mul_f32_e32 v57, 0xbfb8aa3b, v57
	v_exp_f32_e32 v57, v57
	s_nop 0
	v_add_f32_e32 v57, 1.0, v57
	v_rcp_f32_e32 v61, v57
	s_nop 0
	v_pk_mul_f32 v[60:61], v[116:117], v[60:61]
	s_nop 0
	v_pk_mul_f32 v[58:59], v[58:59], v[60:61]
	s_nop 0
	v_cvt_pk_bf16_f32 v57, v58, v59
	v_mov_b64_e32 v[58:59], s[10:11]
	v_mad_i64_i32 v[58:59], s[6:7], v182, s96, v[58:59]
	v_lshl_add_u64 v[58:59], v[174:175], 1, v[58:59]
	global_store_dwordx2 v[58:59], v[56:57], off offset:8
.LBB0_1318:
	s_or_b64 exec, exec, s[2:3]
	v_mov_b32_e32 v121, v120
	v_mov_b32_e32 v56, v120
	v_mov_b32_e32 v57, v120
	v_pk_mul_f32 v[54:55], v[54:55], v[56:57]
	v_pk_mul_f32 v[52:53], v[52:53], v[120:121]
	v_pk_mul_f32 v[50:51], v[50:51], v[56:57]
	v_pk_mul_f32 v[48:49], v[48:49], v[120:121]
	ds_write_b128 v168, v[52:55] offset:1024
	ds_write_b128 v168, v[48:51] offset:17408
	s_and_saveexec_b64 s[2:3], s[0:1]
	s_cbranch_execz .LBB0_1320
	ds_read_b128 v[56:59], v122 offset:16384
	ds_read_b128 v[60:63], v123 offset:16384
	s_waitcnt lgkmcnt(0)
	v_pk_fma_f32 v[62:63], v[90:91], v[62:63], v[94:95]
	v_pk_fma_f32 v[60:61], v[88:89], v[60:61], v[92:93]
	v_pk_fma_f32 v[58:59], v[82:83], v[58:59], v[62:63]
	v_pk_fma_f32 v[56:57], v[80:81], v[56:57], v[60:61]
	v_pk_fma_f32 v[60:61], v[50:51], v[86:87], v[58:59]
	v_pk_fma_f32 v[62:63], v[48:49], v[84:85], v[56:57]
	ds_read_b128 v[48:51], v122
	ds_read_b128 v[56:59], v123
	s_waitcnt lgkmcnt(0)
	v_pk_fma_f32 v[56:57], v[72:73], v[56:57], v[76:77]
	s_nop 0
	v_pk_fma_f32 v[48:49], v[68:69], v[48:49], v[56:57]
	v_pk_fma_f32 v[58:59], v[74:75], v[58:59], v[78:79]
	v_pk_fma_f32 v[48:49], v[52:53], v[64:65], v[48:49]
	v_mul_f32_e32 v52, 0x3d372713, v62
	v_mul_f32_e32 v53, 0x3d372713, v63
	v_fma_f32 v52, v62, v52, 1.0
	v_fma_f32 v53, v63, v53, 1.0
	v_mul_f32_e32 v52, v62, v52
	v_mul_f32_e32 v53, v63, v53
	v_mul_f32_e32 v52, 0x3fcc422a, v52
	v_mul_f32_e32 v53, 0x3fcc422a, v53
	v_mul_f32_e32 v52, 0xbfb8aa3b, v52
	v_mul_f32_e32 v53, 0xbfb8aa3b, v53
	v_exp_f32_e32 v52, v52
	v_exp_f32_e32 v53, v53
	v_pk_fma_f32 v[50:51], v[70:71], v[50:51], v[58:59]
	v_add_f32_e32 v52, 1.0, v52
	v_add_f32_e32 v53, 1.0, v53
	v_rcp_f32_e32 v52, v52
	v_rcp_f32_e32 v53, v53
	v_pk_fma_f32 v[50:51], v[54:55], v[66:67], v[50:51]
	v_pk_mul_f32 v[52:53], v[62:63], v[52:53]
	s_nop 0
	v_pk_mul_f32 v[48:49], v[48:49], v[52:53]
	s_nop 0
	v_cvt_pk_bf16_f32 v48, v48, v49
	v_mul_f32_e32 v49, 0x3d372713, v60
	v_fma_f32 v49, v60, v49, 1.0
	v_mul_f32_e32 v49, v60, v49
	v_mul_f32_e32 v49, 0x3fcc422a, v49
	v_mul_f32_e32 v49, 0xbfb8aa3b, v49
	v_exp_f32_e32 v49, v49
	s_nop 0
	v_add_f32_e32 v49, 1.0, v49
	v_rcp_f32_e32 v52, v49
	v_mul_f32_e32 v49, 0x3d372713, v61
	v_fma_f32 v49, v61, v49, 1.0
	v_mul_f32_e32 v49, v61, v49
	v_mul_f32_e32 v49, 0x3fcc422a, v49
	v_mul_f32_e32 v49, 0xbfb8aa3b, v49
	v_exp_f32_e32 v49, v49
	s_nop 0
	v_add_f32_e32 v49, 1.0, v49
	v_rcp_f32_e32 v53, v49
	s_nop 0
	v_pk_mul_f32 v[52:53], v[60:61], v[52:53]
	s_nop 0
	v_pk_mul_f32 v[50:51], v[50:51], v[52:53]
	s_nop 0
	v_cvt_pk_bf16_f32 v49, v50, v51
	v_mov_b64_e32 v[50:51], s[10:11]
	v_mad_i64_i32 v[50:51], s[6:7], v124, s96, v[50:51]
	v_lshl_add_u64 v[50:51], v[174:175], 1, v[50:51]
	global_store_dwordx2 v[50:51], v[48:49], off offset:8
.LBB0_1320:
	s_or_b64 exec, exec, s[2:3]
	v_mov_b32_e32 v113, v112
	v_mov_b32_e32 v48, v112
	v_mov_b32_e32 v49, v112
	v_pk_mul_f32 v[46:47], v[46:47], v[48:49]
	v_pk_mul_f32 v[44:45], v[44:45], v[112:113]
	v_pk_mul_f32 v[42:43], v[42:43], v[48:49]
	v_pk_mul_f32 v[40:41], v[40:41], v[112:113]
	ds_write_b128 v168, v[44:47]
	ds_write_b128 v168, v[40:43] offset:16384
	s_and_saveexec_b64 s[2:3], s[0:1]
	s_cbranch_execz .LBB0_1322
	ds_read_b128 v[48:51], v185 offset:16384
	ds_read_b128 v[52:55], v183 offset:16384
	s_waitcnt lgkmcnt(0)
	v_pk_fma_f32 v[54:55], v[90:91], v[54:55], v[94:95]
	v_pk_fma_f32 v[52:53], v[88:89], v[52:53], v[92:93]
	v_pk_fma_f32 v[50:51], v[82:83], v[50:51], v[54:55]
	v_pk_fma_f32 v[48:49], v[80:81], v[48:49], v[52:53]
	v_pk_fma_f32 v[52:53], v[42:43], v[86:87], v[50:51]
	v_pk_fma_f32 v[54:55], v[40:41], v[84:85], v[48:49]
	ds_read_b128 v[40:43], v185
	ds_read_b128 v[48:51], v183
	s_waitcnt lgkmcnt(0)
	v_pk_fma_f32 v[48:49], v[72:73], v[48:49], v[76:77]
	s_nop 0
	v_pk_fma_f32 v[40:41], v[68:69], v[40:41], v[48:49]
	v_pk_fma_f32 v[50:51], v[74:75], v[50:51], v[78:79]
	v_pk_fma_f32 v[40:41], v[44:45], v[64:65], v[40:41]
	v_mul_f32_e32 v44, 0x3d372713, v54
	v_mul_f32_e32 v45, 0x3d372713, v55
	v_fma_f32 v44, v54, v44, 1.0
	v_fma_f32 v45, v55, v45, 1.0
	v_mul_f32_e32 v44, v54, v44
	v_mul_f32_e32 v45, v55, v45
	v_mul_f32_e32 v44, 0x3fcc422a, v44
	v_mul_f32_e32 v45, 0x3fcc422a, v45
	v_mul_f32_e32 v44, 0xbfb8aa3b, v44
	v_mul_f32_e32 v45, 0xbfb8aa3b, v45
	v_exp_f32_e32 v44, v44
	v_exp_f32_e32 v45, v45
	v_pk_fma_f32 v[42:43], v[70:71], v[42:43], v[50:51]
	v_add_f32_e32 v44, 1.0, v44
	v_add_f32_e32 v45, 1.0, v45
	v_rcp_f32_e32 v44, v44
	v_rcp_f32_e32 v45, v45
	v_pk_fma_f32 v[42:43], v[46:47], v[66:67], v[42:43]
	v_pk_mul_f32 v[44:45], v[54:55], v[44:45]
	s_nop 0
	v_pk_mul_f32 v[40:41], v[40:41], v[44:45]
	s_nop 0
	v_cvt_pk_bf16_f32 v40, v40, v41
	v_mul_f32_e32 v41, 0x3d372713, v52
	v_fma_f32 v41, v52, v41, 1.0
	v_mul_f32_e32 v41, v52, v41
	v_mul_f32_e32 v41, 0x3fcc422a, v41
	v_mul_f32_e32 v41, 0xbfb8aa3b, v41
	v_exp_f32_e32 v41, v41
	s_nop 0
	v_add_f32_e32 v41, 1.0, v41
	v_rcp_f32_e32 v44, v41
	v_mul_f32_e32 v41, 0x3d372713, v53
	v_fma_f32 v41, v53, v41, 1.0
	v_mul_f32_e32 v41, v53, v41
	v_mul_f32_e32 v41, 0x3fcc422a, v41
	v_mul_f32_e32 v41, 0xbfb8aa3b, v41
	v_exp_f32_e32 v41, v41
	s_nop 0
	v_add_f32_e32 v41, 1.0, v41
	v_rcp_f32_e32 v45, v41
	s_nop 0
	v_pk_mul_f32 v[44:45], v[52:53], v[44:45]
	s_nop 0
	v_pk_mul_f32 v[42:43], v[42:43], v[44:45]
	s_nop 0
	v_cvt_pk_bf16_f32 v41, v42, v43
	v_mov_b64_e32 v[42:43], s[10:11]
	v_mad_i64_i32 v[42:43], s[6:7], v114, s96, v[42:43]
	v_lshl_add_u64 v[42:43], v[174:175], 1, v[42:43]
	global_store_dwordx2 v[42:43], v[40:41], off offset:8
.LBB0_1322:
	s_or_b64 exec, exec, s[2:3]
	v_mov_b32_e32 v105, v104
	v_mov_b32_e32 v40, v104
	v_mov_b32_e32 v41, v104
	v_pk_mul_f32 v[38:39], v[38:39], v[40:41]
	v_pk_mul_f32 v[36:37], v[36:37], v[104:105]
	v_pk_mul_f32 v[34:35], v[34:35], v[40:41]
	v_pk_mul_f32 v[32:33], v[32:33], v[104:105]
	ds_write_b128 v168, v[36:39] offset:1024
	ds_write_b128 v168, v[32:35] offset:17408
	s_and_saveexec_b64 s[2:3], s[0:1]
	s_cbranch_execz .LBB0_1324
	ds_read_b128 v[40:43], v122 offset:16384
	ds_read_b128 v[44:47], v123 offset:16384
	s_waitcnt lgkmcnt(0)
	v_pk_fma_f32 v[46:47], v[90:91], v[46:47], v[94:95]
	v_pk_fma_f32 v[44:45], v[88:89], v[44:45], v[92:93]
	v_pk_fma_f32 v[42:43], v[82:83], v[42:43], v[46:47]
	v_pk_fma_f32 v[40:41], v[80:81], v[40:41], v[44:45]
	v_pk_fma_f32 v[44:45], v[34:35], v[86:87], v[42:43]
	v_pk_fma_f32 v[46:47], v[32:33], v[84:85], v[40:41]
	ds_read_b128 v[32:35], v122
	ds_read_b128 v[40:43], v123
	s_waitcnt lgkmcnt(0)
	v_pk_fma_f32 v[40:41], v[72:73], v[40:41], v[76:77]
	s_nop 0
	v_pk_fma_f32 v[32:33], v[68:69], v[32:33], v[40:41]
	v_pk_fma_f32 v[42:43], v[74:75], v[42:43], v[78:79]
	v_pk_fma_f32 v[32:33], v[36:37], v[64:65], v[32:33]
	v_mul_f32_e32 v36, 0x3d372713, v46
	v_mul_f32_e32 v37, 0x3d372713, v47
	v_fma_f32 v36, v46, v36, 1.0
	v_fma_f32 v37, v47, v37, 1.0
	v_mul_f32_e32 v36, v46, v36
	v_mul_f32_e32 v37, v47, v37
	v_mul_f32_e32 v36, 0x3fcc422a, v36
	v_mul_f32_e32 v37, 0x3fcc422a, v37
	v_mul_f32_e32 v36, 0xbfb8aa3b, v36
	v_mul_f32_e32 v37, 0xbfb8aa3b, v37
	v_exp_f32_e32 v36, v36
	v_exp_f32_e32 v37, v37
	v_pk_fma_f32 v[34:35], v[70:71], v[34:35], v[42:43]
	v_add_f32_e32 v36, 1.0, v36
	v_add_f32_e32 v37, 1.0, v37
	v_rcp_f32_e32 v36, v36
	v_rcp_f32_e32 v37, v37
	v_pk_fma_f32 v[34:35], v[38:39], v[66:67], v[34:35]
	v_pk_mul_f32 v[36:37], v[46:47], v[36:37]
	s_nop 0
	v_pk_mul_f32 v[32:33], v[32:33], v[36:37]
	s_nop 0
	v_cvt_pk_bf16_f32 v32, v32, v33
	v_mul_f32_e32 v33, 0x3d372713, v44
	v_fma_f32 v33, v44, v33, 1.0
	v_mul_f32_e32 v33, v44, v33
	v_mul_f32_e32 v33, 0x3fcc422a, v33
	v_mul_f32_e32 v33, 0xbfb8aa3b, v33
	v_exp_f32_e32 v33, v33
	s_nop 0
	v_add_f32_e32 v33, 1.0, v33
	v_rcp_f32_e32 v36, v33
	v_mul_f32_e32 v33, 0x3d372713, v45
	v_fma_f32 v33, v45, v33, 1.0
	v_mul_f32_e32 v33, v45, v33
	v_mul_f32_e32 v33, 0x3fcc422a, v33
	v_mul_f32_e32 v33, 0xbfb8aa3b, v33
	v_exp_f32_e32 v33, v33
	s_nop 0
	v_add_f32_e32 v33, 1.0, v33
	v_rcp_f32_e32 v37, v33
	s_nop 0
	v_pk_mul_f32 v[36:37], v[44:45], v[36:37]
	s_nop 0
	v_pk_mul_f32 v[34:35], v[34:35], v[36:37]
	s_nop 0
	v_cvt_pk_bf16_f32 v33, v34, v35
	v_mov_b64_e32 v[34:35], s[10:11]
	v_mad_i64_i32 v[34:35], s[6:7], v106, s96, v[34:35]
	v_lshl_add_u64 v[34:35], v[174:175], 1, v[34:35]
	global_store_dwordx2 v[34:35], v[32:33], off offset:8
.LBB0_1324:
	s_or_b64 exec, exec, s[2:3]
	v_mov_b32_e32 v97, v96
	v_mov_b32_e32 v32, v96
	v_mov_b32_e32 v33, v96
	v_pk_mul_f32 v[30:31], v[30:31], v[32:33]
	v_pk_mul_f32 v[28:29], v[28:29], v[96:97]
	v_pk_mul_f32 v[26:27], v[26:27], v[32:33]
	v_pk_mul_f32 v[24:25], v[24:25], v[96:97]
	ds_write_b128 v168, v[28:31]
	ds_write_b128 v168, v[24:27] offset:16384
	s_and_saveexec_b64 s[2:3], s[8:9]
	s_cbranch_execz .LBB0_1326
	ds_read_b128 v[32:35], v185 offset:16384
	ds_read_b128 v[36:39], v183 offset:16384
	s_waitcnt lgkmcnt(0)
	v_pk_fma_f32 v[38:39], v[90:91], v[38:39], v[94:95]
	v_pk_fma_f32 v[36:37], v[88:89], v[36:37], v[92:93]
	v_pk_fma_f32 v[34:35], v[82:83], v[34:35], v[38:39]
	v_pk_fma_f32 v[32:33], v[80:81], v[32:33], v[36:37]
	v_pk_fma_f32 v[36:37], v[26:27], v[86:87], v[34:35]
	v_pk_fma_f32 v[38:39], v[24:25], v[84:85], v[32:33]
	ds_read_b128 v[24:27], v185
	ds_read_b128 v[32:35], v183
	s_waitcnt lgkmcnt(0)
	v_pk_fma_f32 v[32:33], v[72:73], v[32:33], v[76:77]
	s_nop 0
	v_pk_fma_f32 v[24:25], v[68:69], v[24:25], v[32:33]
	v_pk_fma_f32 v[34:35], v[74:75], v[34:35], v[78:79]
	v_pk_fma_f32 v[24:25], v[28:29], v[64:65], v[24:25]
	v_mul_f32_e32 v28, 0x3d372713, v38
	v_mul_f32_e32 v29, 0x3d372713, v39
	v_fma_f32 v28, v38, v28, 1.0
	v_fma_f32 v29, v39, v29, 1.0
	v_mul_f32_e32 v28, v38, v28
	v_mul_f32_e32 v29, v39, v29
	v_mul_f32_e32 v28, 0x3fcc422a, v28
	v_mul_f32_e32 v29, 0x3fcc422a, v29
	v_mul_f32_e32 v28, 0xbfb8aa3b, v28
	v_mul_f32_e32 v29, 0xbfb8aa3b, v29
	v_exp_f32_e32 v28, v28
	v_exp_f32_e32 v29, v29
	v_pk_fma_f32 v[26:27], v[70:71], v[26:27], v[34:35]
	v_add_f32_e32 v28, 1.0, v28
	v_add_f32_e32 v29, 1.0, v29
	v_rcp_f32_e32 v28, v28
	v_rcp_f32_e32 v29, v29
	v_pk_fma_f32 v[26:27], v[30:31], v[66:67], v[26:27]
	v_pk_mul_f32 v[28:29], v[38:39], v[28:29]
	s_nop 0
	v_pk_mul_f32 v[24:25], v[24:25], v[28:29]
	s_nop 0
	v_cvt_pk_bf16_f32 v24, v24, v25
	v_mul_f32_e32 v25, 0x3d372713, v36
	v_fma_f32 v25, v36, v25, 1.0
	v_mul_f32_e32 v25, v36, v25
	v_mul_f32_e32 v25, 0x3fcc422a, v25
	v_mul_f32_e32 v25, 0xbfb8aa3b, v25
	v_exp_f32_e32 v25, v25
	s_nop 0
	v_add_f32_e32 v25, 1.0, v25
	v_rcp_f32_e32 v28, v25
	v_mul_f32_e32 v25, 0x3d372713, v37
	v_fma_f32 v25, v37, v25, 1.0
	v_mul_f32_e32 v25, v37, v25
	v_mul_f32_e32 v25, 0x3fcc422a, v25
	v_mul_f32_e32 v25, 0xbfb8aa3b, v25
	v_exp_f32_e32 v25, v25
	s_nop 0
	v_add_f32_e32 v25, 1.0, v25
	v_rcp_f32_e32 v29, v25
	s_nop 0
	v_pk_mul_f32 v[28:29], v[36:37], v[28:29]
	s_nop 0
	v_pk_mul_f32 v[26:27], v[26:27], v[28:29]
	s_nop 0
	v_cvt_pk_bf16_f32 v25, v26, v27
	v_mov_b64_e32 v[26:27], s[10:11]
	v_mad_i64_i32 v[26:27], s[6:7], v184, s96, v[26:27]
	v_lshl_add_u64 v[26:27], v[174:175], 1, v[26:27]
	global_store_dwordx2 v[26:27], v[24:25], off offset:8
.LBB0_1326:
	s_or_b64 exec, exec, s[2:3]
	v_mov_b32_e32 v99, v98
	v_mov_b32_e32 v24, v98
	v_mov_b32_e32 v25, v98
	v_pk_mul_f32 v[22:23], v[22:23], v[24:25]
	v_pk_mul_f32 v[20:21], v[20:21], v[98:99]
	v_pk_mul_f32 v[18:19], v[18:19], v[24:25]
	v_pk_mul_f32 v[16:17], v[16:17], v[98:99]
	ds_write_b128 v168, v[20:23] offset:1024
	ds_write_b128 v168, v[16:19] offset:17408
	s_and_saveexec_b64 s[2:3], s[0:1]
	s_cbranch_execz .LBB0_1328
	ds_read_b128 v[24:27], v122 offset:16384
	ds_read_b128 v[28:31], v123 offset:16384
	s_waitcnt lgkmcnt(0)
	v_pk_fma_f32 v[30:31], v[90:91], v[30:31], v[94:95]
	v_pk_fma_f32 v[28:29], v[88:89], v[28:29], v[92:93]
	v_pk_fma_f32 v[26:27], v[82:83], v[26:27], v[30:31]
	v_pk_fma_f32 v[24:25], v[80:81], v[24:25], v[28:29]
	v_pk_fma_f32 v[28:29], v[18:19], v[86:87], v[26:27]
	v_pk_fma_f32 v[30:31], v[16:17], v[84:85], v[24:25]
	ds_read_b128 v[16:19], v122
	ds_read_b128 v[24:27], v123
	s_waitcnt lgkmcnt(0)
	v_pk_fma_f32 v[24:25], v[72:73], v[24:25], v[76:77]
	s_nop 0
	v_pk_fma_f32 v[16:17], v[68:69], v[16:17], v[24:25]
	v_pk_fma_f32 v[26:27], v[74:75], v[26:27], v[78:79]
	v_pk_fma_f32 v[16:17], v[20:21], v[64:65], v[16:17]
	v_mul_f32_e32 v20, 0x3d372713, v30
	v_mul_f32_e32 v21, 0x3d372713, v31
	v_fma_f32 v20, v30, v20, 1.0
	v_fma_f32 v21, v31, v21, 1.0
	v_mul_f32_e32 v20, v30, v20
	v_mul_f32_e32 v21, v31, v21
	v_mul_f32_e32 v20, 0x3fcc422a, v20
	v_mul_f32_e32 v21, 0x3fcc422a, v21
	v_mul_f32_e32 v20, 0xbfb8aa3b, v20
	v_mul_f32_e32 v21, 0xbfb8aa3b, v21
	v_exp_f32_e32 v20, v20
	v_exp_f32_e32 v21, v21
	v_pk_fma_f32 v[18:19], v[70:71], v[18:19], v[26:27]
	v_add_f32_e32 v20, 1.0, v20
	v_add_f32_e32 v21, 1.0, v21
	v_rcp_f32_e32 v20, v20
	v_rcp_f32_e32 v21, v21
	v_pk_fma_f32 v[18:19], v[22:23], v[66:67], v[18:19]
	v_pk_mul_f32 v[20:21], v[30:31], v[20:21]
	s_nop 0
	v_pk_mul_f32 v[16:17], v[16:17], v[20:21]
	s_nop 0
	v_cvt_pk_bf16_f32 v16, v16, v17
	v_mul_f32_e32 v17, 0x3d372713, v28
	v_fma_f32 v17, v28, v17, 1.0
	v_mul_f32_e32 v17, v28, v17
	v_mul_f32_e32 v17, 0x3fcc422a, v17
	v_mul_f32_e32 v17, 0xbfb8aa3b, v17
	v_exp_f32_e32 v17, v17
	s_nop 0
	v_add_f32_e32 v17, 1.0, v17
	v_rcp_f32_e32 v20, v17
	v_mul_f32_e32 v17, 0x3d372713, v29
	v_fma_f32 v17, v29, v17, 1.0
	v_mul_f32_e32 v17, v29, v17
	v_mul_f32_e32 v17, 0x3fcc422a, v17
	v_mul_f32_e32 v17, 0xbfb8aa3b, v17
	v_exp_f32_e32 v17, v17
	s_nop 0
	v_add_f32_e32 v17, 1.0, v17
	v_rcp_f32_e32 v21, v17
	s_nop 0
	v_pk_mul_f32 v[20:21], v[28:29], v[20:21]
	s_nop 0
	v_pk_mul_f32 v[18:19], v[18:19], v[20:21]
	s_nop 0
	v_cvt_pk_bf16_f32 v17, v18, v19
	v_mov_b64_e32 v[18:19], s[10:11]
	v_mad_i64_i32 v[18:19], s[6:7], v101, s96, v[18:19]
	v_lshl_add_u64 v[18:19], v[174:175], 1, v[18:19]
	global_store_dwordx2 v[18:19], v[16:17], off offset:8
.LBB0_1328:
	s_or_b64 exec, exec, s[2:3]
	v_mov_b32_e32 v101, v100
	v_mov_b32_e32 v16, v100
	v_mov_b32_e32 v17, v100
	v_pk_mul_f32 v[14:15], v[14:15], v[16:17]
	v_pk_mul_f32 v[12:13], v[12:13], v[100:101]
	v_pk_mul_f32 v[10:11], v[10:11], v[16:17]
	v_pk_mul_f32 v[8:9], v[8:9], v[100:101]
	ds_write_b128 v168, v[12:15]
	ds_write_b128 v168, v[8:11] offset:16384
	s_and_saveexec_b64 s[2:3], s[0:1]
	s_cbranch_execz .LBB0_1330
	ds_read_b128 v[16:19], v185 offset:16384
	ds_read_b128 v[20:23], v183 offset:16384
	s_waitcnt lgkmcnt(0)
	v_pk_fma_f32 v[22:23], v[90:91], v[22:23], v[94:95]
	v_pk_fma_f32 v[20:21], v[88:89], v[20:21], v[92:93]
	v_pk_fma_f32 v[18:19], v[82:83], v[18:19], v[22:23]
	v_pk_fma_f32 v[16:17], v[80:81], v[16:17], v[20:21]
	v_pk_fma_f32 v[20:21], v[10:11], v[86:87], v[18:19]
	v_pk_fma_f32 v[22:23], v[8:9], v[84:85], v[16:17]
	ds_read_b128 v[8:11], v185
	ds_read_b128 v[16:19], v183
	s_waitcnt lgkmcnt(0)
	v_pk_fma_f32 v[16:17], v[72:73], v[16:17], v[76:77]
	s_nop 0
	v_pk_fma_f32 v[8:9], v[68:69], v[8:9], v[16:17]
	v_pk_fma_f32 v[18:19], v[74:75], v[18:19], v[78:79]
	v_pk_fma_f32 v[8:9], v[12:13], v[64:65], v[8:9]
	v_mul_f32_e32 v12, 0x3d372713, v22
	v_mul_f32_e32 v13, 0x3d372713, v23
	v_fma_f32 v12, v22, v12, 1.0
	v_fma_f32 v13, v23, v13, 1.0
	v_mul_f32_e32 v12, v22, v12
	v_mul_f32_e32 v13, v23, v13
	v_mul_f32_e32 v12, 0x3fcc422a, v12
	v_mul_f32_e32 v13, 0x3fcc422a, v13
	v_mul_f32_e32 v12, 0xbfb8aa3b, v12
	v_mul_f32_e32 v13, 0xbfb8aa3b, v13
	v_exp_f32_e32 v12, v12
	v_exp_f32_e32 v13, v13
	v_pk_fma_f32 v[10:11], v[70:71], v[10:11], v[18:19]
	v_add_f32_e32 v12, 1.0, v12
	v_add_f32_e32 v13, 1.0, v13
	v_rcp_f32_e32 v12, v12
	v_rcp_f32_e32 v13, v13
	v_pk_fma_f32 v[10:11], v[14:15], v[66:67], v[10:11]
	v_pk_mul_f32 v[12:13], v[22:23], v[12:13]
	s_nop 0
	v_pk_mul_f32 v[8:9], v[8:9], v[12:13]
	s_nop 0
	v_cvt_pk_bf16_f32 v8, v8, v9
	v_mul_f32_e32 v9, 0x3d372713, v20
	v_fma_f32 v9, v20, v9, 1.0
	v_mul_f32_e32 v9, v20, v9
	v_mul_f32_e32 v9, 0x3fcc422a, v9
	v_mul_f32_e32 v9, 0xbfb8aa3b, v9
	v_exp_f32_e32 v9, v9
	s_nop 0
	v_add_f32_e32 v9, 1.0, v9
	v_rcp_f32_e32 v12, v9
	v_mul_f32_e32 v9, 0x3d372713, v21
	v_fma_f32 v9, v21, v9, 1.0
	v_mul_f32_e32 v9, v21, v9
	v_mul_f32_e32 v9, 0x3fcc422a, v9
	v_mul_f32_e32 v9, 0xbfb8aa3b, v9
	v_exp_f32_e32 v9, v9
	s_nop 0
	v_add_f32_e32 v9, 1.0, v9
	v_rcp_f32_e32 v13, v9
	s_nop 0
	v_pk_mul_f32 v[12:13], v[20:21], v[12:13]
	s_nop 0
	v_pk_mul_f32 v[10:11], v[10:11], v[12:13]
	s_nop 0
	v_cvt_pk_bf16_f32 v9, v10, v11
	v_mov_b64_e32 v[10:11], s[10:11]
	v_mad_i64_i32 v[10:11], s[6:7], v103, s96, v[10:11]
	v_lshl_add_u64 v[10:11], v[174:175], 1, v[10:11]
	global_store_dwordx2 v[10:11], v[8:9], off offset:8
